# topk key-tile staging de-serialized: 8 tile loads issued together before the barrier, counted vmcnt waits, then LDS writes
# speedup vs baseline: 1.0071x; 1.0071x over previous
; DI void phase_peer_topk(const Params& P, int layer, char* smem) {
;     ...
;         __syncthreads();
; #pragma unroll
;         for (int i = 0; i < 8; ++i) {
;           int id = tid + i * 256;
;           int pp = id >> 10, rem = id & 1023;
;           const float4* src = (const float4*)(P.peer_keys + ((((size_t)layer * 8 + head) * 2 + pp) * 128 + nh * 64) * 64) + rem;
;           ((float4*)kl)[id] = *src;
;         }
;         __syncthreads();
.LBB0_43:
	s_waitcnt lgkmcnt(0)
	s_lshl_b32 s4, s16, 12
	s_xor_b64 s[6:7], s[12:13], -1
	s_lshl_b64 s[12:13], s[4:5], 2
	v_lshl_add_u64 v[144:145], v[108:109], 0, s[12:13]
	global_load_dwordx4 v[146:149], v[144:145], off
	v_lshl_add_u64 v[144:145], v[110:111], 0, s[12:13]
	global_load_dwordx4 v[150:153], v[144:145], off
	v_lshl_add_u64 v[144:145], v[112:113], 0, s[12:13]
	global_load_dwordx4 v[154:157], v[144:145], off
	v_lshl_add_u64 v[144:145], v[114:115], 0, s[12:13]
	global_load_dwordx4 v[158:161], v[144:145], off
	v_lshl_add_u64 v[144:145], v[116:117], 0, s[12:13]
	global_load_dwordx4 v[162:165], v[144:145], off
	v_lshl_add_u64 v[144:145], v[118:119], 0, s[12:13]
	global_load_dwordx4 v[174:177], v[144:145], off
	v_lshl_add_u64 v[144:145], v[120:121], 0, s[12:13]
	global_load_dwordx4 v[178:181], v[144:145], off
	v_lshl_add_u64 v[144:145], v[122:123], 0, s[12:13]
	global_load_dwordx4 v[182:185], v[144:145], off
	v_lshl_add_u32 v143, s16, 6, v107
	s_mov_b32 s4, 0
	s_mov_b64 s[12:13], -1
	s_barrier
	s_waitcnt vmcnt(7)
	ds_write_b128 v70, v[146:149]
	s_waitcnt vmcnt(6)
	ds_write_b128 v125, v[150:153]
	s_waitcnt vmcnt(5)
	ds_write_b128 v126, v[154:157]
	s_waitcnt vmcnt(4)
	ds_write_b128 v127, v[158:161]
	s_waitcnt vmcnt(3)
	ds_write_b128 v128, v[162:165]
	s_waitcnt vmcnt(2)
	ds_write_b128 v129, v[174:177]
	s_waitcnt vmcnt(1)
	ds_write_b128 v130, v[178:181]
	s_waitcnt vmcnt(0)
	ds_write_b128 v131, v[182:185]
	s_waitcnt lgkmcnt(0)
	s_barrier
